# combination: dprep queue prefetch, mix sample-tile rebalancing, workgroup stagger in the up phase
# baseline (speedup 1.0000x reference)
.LBB0_9:
	s_mul_hi_i32 s0, s24, 0x38e38e39
	s_lshr_b32 s1, s0, 31
	s_ashr_i32 s0, s0, 1
	s_add_i32 s2, s0, s1
	s_mul_i32 s0, s2, 9
	s_sub_i32 s4, s24, s0
	s_lshl_b32 s0, s2, 10
	s_ashr_i32 s1, s0, 31
	v_writelane_b32 v252, s0, 54
	s_nop 1
	v_writelane_b32 v252, s1, 55
	s_lshl_b32 s0, s2, 1
	s_ashr_i32 s1, s0, 31
	v_writelane_b32 v252, s0, 56
	s_nop 1
	v_writelane_b32 v252, s1, 57
	s_add_i32 s0, s24, 8
	s_cmp_lt_u32 s0, 17
	v_writelane_b32 v252, s24, 58
	s_cselect_b64 s[0:1], -1, 0
	v_writelane_b32 v252, s0, 59
	s_ashr_i32 s3, s2, 31
	s_cmp_lt_i32 s4, 4
	v_writelane_b32 v252, s1, 60
	v_writelane_b32 v252, s2, 61
	s_mul_i32 s0, s2, 0x108
	s_nop 0
	v_writelane_b32 v252, s3, 62
	v_writelane_b32 v252, s0, 63
	s_mov_b64 s[2:3], 0
	s_nop 0
	v_writelane_b32 v253, s1, 0
	v_writelane_b32 v253, s4, 1
	s_mov_b64 s[4:5], 0
	v_writelane_b32 v253, s4, 2
	s_mov_b64 s[0:1], -1
	s_nop 0
	v_writelane_b32 v253, s5, 3
	s_cbranch_scc1 .LBB0_157
	v_readlane_b32 s0, v253, 1
	s_cmp_gt_i32 s0, 5
	s_cbranch_scc0 .LBB0_27
	s_cmp_gt_i32 s0, 6
	s_cbranch_scc0 .LBB0_28
	s_cmp_eq_u32 s0, 7
	s_mov_b64 s[0:1], -1
	s_cbranch_scc0 .LBB0_33
	v_readlane_b32 s16, v251, 1
	v_readlane_b32 s30, v251, 15
	v_readlane_b32 s31, v251, 16
	v_readlane_b32 s8, v251, 21
	s_mov_b64 s[0:1], s[30:31]
	s_waitcnt vmcnt(0)
	v_mov_b32_e32 v2, v211
	v_readlane_b32 s9, v251, 22
	v_readlane_b32 s10, v252, 34
	v_readlane_b32 s18, v251, 3
	s_load_dword s10, s[8:9], 0x0
	v_readlane_b32 s19, v251, 4
	s_add_u32 s18, s0, 0x1f80000
	v_readlane_b32 s20, v251, 5
	s_addc_u32 s19, s1, 0
	v_readlane_b32 s21, v251, 6
	s_add_u32 s20, s0, 0xf00000
	s_addc_u32 s21, s1, 0
	v_readlane_b32 s11, v252, 35
	v_readlane_b32 s22, v251, 7
	s_add_u32 s4, s0, 0x6080000
	v_and_b32_e32 v0, 15, v2
	s_waitcnt lgkmcnt(0)
	v_writelane_b32 v252, s10, 34
	v_ashrrev_i32_e32 v3, 2, v2
	s_movk_i32 s8, 0xffc0
	v_lshrrev_b32_e32 v2, 2, v2
	s_addc_u32 s5, s1, 0
	v_writelane_b32 v252, s11, 35
	v_and_or_b32 v0, v3, s8, v0
	v_and_b32_e32 v142, 60, v2
	s_mov_b32 s22, 0
	v_readlane_b32 s17, v251, 2
	v_readlane_b32 s23, v251, 8
	v_readlane_b32 s24, v251, 9
	v_readlane_b32 s25, v251, 10
	v_readlane_b32 s26, v251, 11
	v_readlane_b32 s27, v251, 12
	v_readlane_b32 s28, v251, 13
	v_readlane_b32 s29, v251, 14
	v_readlane_b32 s8, v251, 0
	s_cmp_lt_u32 s8, 44
	s_cbranch_scc1 .Lstag_up_done
	s_lshr_b32 s8, s8, 3
	s_and_b32 s8, s8, 3
	s_mul_i32 s8, s8, 3
.Lstag_up_loop:
	s_cmp_eq_u32 s8, 0
	s_cbranch_scc1 .Lstag_up_done
	s_sleep 127
	s_sub_u32 s8, s8, 1
	s_branch .Lstag_up_loop
.Lstag_up_done:
	s_branch .LBB0_16
.LBB0_14:
	s_or_b64 exec, exec, s[10:11]
	v_mul_f32_e32 v133, 0xbfb8aa3b, v126
	v_exp_f32_e32 v133, v133
	v_lshl_or_b32 v130, s23, 7, v142
	v_ashrrev_i32_e32 v131, 31, v130
	v_add_u32_e32 v132, s8, v0
	v_add_f32_e32 v133, 1.0, v133
	v_rcp_f32_e32 v134, v133
	v_mul_f32_e32 v133, 0xbfb8aa3b, v127
	v_exp_f32_e32 v133, v133
	v_lshl_add_u64 v[130:131], v[130:131], 1, s[4:5]
	s_movk_i32 s10, 0x1600
	s_add_i32 s22, s22, 1
	v_add_f32_e32 v133, 1.0, v133
	v_rcp_f32_e32 v135, v133
	s_nop 0
	v_pk_mul_f32 v[126:127], v[126:127], v[134:135]
	s_nop 0
	v_pk_mul_f32 v[122:123], v[122:123], v[126:127]
	s_nop 0
	v_cvt_pk_bf16_f32 v126, v122, v123
	v_mul_f32_e32 v122, 0xbfb8aa3b, v128
	v_mul_f32_e32 v123, 0xbfb8aa3b, v129
	v_exp_f32_e32 v122, v122
	v_exp_f32_e32 v123, v123
	v_add_f32_e32 v122, 1.0, v122
	v_add_f32_e32 v123, 1.0, v123
	v_rcp_f32_e32 v122, v122
	v_rcp_f32_e32 v123, v123
	s_nop 0
	v_pk_mul_f32 v[122:123], v[128:129], v[122:123]
	s_nop 0
	v_pk_mul_f32 v[122:123], v[124:125], v[122:123]
	v_mul_f32_e32 v124, 0xbfb8aa3b, v118
	v_mul_f32_e32 v125, 0xbfb8aa3b, v119
	v_exp_f32_e32 v124, v124
	v_exp_f32_e32 v125, v125
	v_cvt_pk_bf16_f32 v127, v122, v123
	v_mad_i64_i32 v[122:123], s[8:9], v132, s10, v[130:131]
	v_add_f32_e32 v124, 1.0, v124
	v_add_f32_e32 v125, 1.0, v125
	v_rcp_f32_e32 v124, v124
	v_rcp_f32_e32 v125, v125
	s_waitcnt vmcnt(0)
	flat_store_dwordx2 v[122:123], v[126:127]
	v_or_b32_e32 v126, 16, v132
	v_pk_mul_f32 v[118:119], v[118:119], v[124:125]
	s_nop 0
	v_pk_mul_f32 v[114:115], v[114:115], v[118:119]
	s_nop 0
	v_cvt_pk_bf16_f32 v118, v114, v115
	v_mul_f32_e32 v114, 0xbfb8aa3b, v120
	v_mul_f32_e32 v115, 0xbfb8aa3b, v121
	v_exp_f32_e32 v114, v114
	v_exp_f32_e32 v115, v115
	v_add_f32_e32 v114, 1.0, v114
	v_add_f32_e32 v115, 1.0, v115
	v_rcp_f32_e32 v114, v114
	v_rcp_f32_e32 v115, v115
	s_nop 0
	v_pk_mul_f32 v[114:115], v[120:121], v[114:115]
	s_nop 0
	v_pk_mul_f32 v[114:115], v[116:117], v[114:115]
	v_mul_f32_e32 v116, 0xbfb8aa3b, v110
	v_mul_f32_e32 v117, 0xbfb8aa3b, v111
	v_exp_f32_e32 v116, v116
	v_exp_f32_e32 v117, v117
	v_cvt_pk_bf16_f32 v119, v114, v115
	v_mad_i64_i32 v[114:115], s[8:9], v126, s10, v[130:131]
	v_add_f32_e32 v116, 1.0, v116
	v_add_f32_e32 v117, 1.0, v117
	v_rcp_f32_e32 v116, v116
	v_rcp_f32_e32 v117, v117
	flat_store_dwordx2 v[114:115], v[118:119]
	v_or_b32_e32 v118, 32, v132
	v_pk_mul_f32 v[110:111], v[110:111], v[116:117]
	s_nop 0
	v_pk_mul_f32 v[106:107], v[106:107], v[110:111]
	s_nop 0
	v_cvt_pk_bf16_f32 v110, v106, v107
	v_mul_f32_e32 v106, 0xbfb8aa3b, v112
	v_mul_f32_e32 v107, 0xbfb8aa3b, v113
	v_exp_f32_e32 v106, v106
	v_exp_f32_e32 v107, v107
	v_add_f32_e32 v106, 1.0, v106
	v_add_f32_e32 v107, 1.0, v107
	v_rcp_f32_e32 v106, v106
	v_rcp_f32_e32 v107, v107
	s_nop 0
	v_pk_mul_f32 v[106:107], v[112:113], v[106:107]
	s_nop 0
	v_pk_mul_f32 v[106:107], v[108:109], v[106:107]
	v_mul_f32_e32 v108, 0xbfb8aa3b, v102
	v_mul_f32_e32 v109, 0xbfb8aa3b, v103
	v_exp_f32_e32 v108, v108
	v_exp_f32_e32 v109, v109
	v_cvt_pk_bf16_f32 v111, v106, v107
	v_mad_i64_i32 v[106:107], s[8:9], v118, s10, v[130:131]
	v_add_f32_e32 v108, 1.0, v108
	v_add_f32_e32 v109, 1.0, v109
	v_rcp_f32_e32 v108, v108
	v_rcp_f32_e32 v109, v109
	flat_store_dwordx2 v[106:107], v[110:111]
	v_or_b32_e32 v110, 48, v132
	v_pk_mul_f32 v[102:103], v[102:103], v[108:109]
	s_nop 0
	v_pk_mul_f32 v[98:99], v[98:99], v[102:103]
	s_nop 0
	v_cvt_pk_bf16_f32 v102, v98, v99
	v_mul_f32_e32 v98, 0xbfb8aa3b, v104
	v_mul_f32_e32 v99, 0xbfb8aa3b, v105
	v_exp_f32_e32 v98, v98
	v_exp_f32_e32 v99, v99
	v_add_f32_e32 v98, 1.0, v98
	v_add_f32_e32 v99, 1.0, v99
	v_rcp_f32_e32 v98, v98
	v_rcp_f32_e32 v99, v99
	s_nop 0
	v_pk_mul_f32 v[98:99], v[104:105], v[98:99]
	s_nop 0
	v_pk_mul_f32 v[98:99], v[100:101], v[98:99]
	v_mul_f32_e32 v100, 0xbfb8aa3b, v94
	v_mul_f32_e32 v101, 0xbfb8aa3b, v95
	v_exp_f32_e32 v100, v100
	v_exp_f32_e32 v101, v101
	v_cvt_pk_bf16_f32 v103, v98, v99
	v_mad_i64_i32 v[98:99], s[8:9], v110, s10, v[130:131]
	v_add_f32_e32 v100, 1.0, v100
	v_add_f32_e32 v101, 1.0, v101
	v_rcp_f32_e32 v100, v100
	v_rcp_f32_e32 v101, v101
	flat_store_dwordx2 v[98:99], v[102:103]
	v_pk_mul_f32 v[94:95], v[94:95], v[100:101]
	s_nop 0
	v_pk_mul_f32 v[90:91], v[90:91], v[94:95]
	s_nop 0
	v_cvt_pk_bf16_f32 v90, v90, v91
	v_mul_f32_e32 v91, 0xbfb8aa3b, v96
	v_exp_f32_e32 v91, v91
	s_nop 0
	v_add_f32_e32 v91, 1.0, v91
	v_rcp_f32_e32 v94, v91
	v_mul_f32_e32 v91, 0xbfb8aa3b, v97
	v_exp_f32_e32 v91, v91
	s_nop 0
	v_add_f32_e32 v91, 1.0, v91
	v_rcp_f32_e32 v95, v91
	s_nop 0
	v_pk_mul_f32 v[94:95], v[96:97], v[94:95]
	s_nop 0
	v_pk_mul_f32 v[92:93], v[92:93], v[94:95]
	s_nop 0
	v_cvt_pk_bf16_f32 v91, v92, v93
	flat_store_dwordx2 v[122:123], v[90:91] offset:128
	v_mul_f32_e32 v90, 0xbfb8aa3b, v86
	v_mul_f32_e32 v91, 0xbfb8aa3b, v87
	v_exp_f32_e32 v90, v90
	v_exp_f32_e32 v91, v91
	v_add_f32_e32 v90, 1.0, v90
	v_add_f32_e32 v91, 1.0, v91
	v_rcp_f32_e32 v90, v90
	v_rcp_f32_e32 v91, v91
	s_nop 0
	v_pk_mul_f32 v[86:87], v[86:87], v[90:91]
	s_nop 0
	v_pk_mul_f32 v[82:83], v[82:83], v[86:87]
	s_nop 0
	v_cvt_pk_bf16_f32 v82, v82, v83
	v_mul_f32_e32 v83, 0xbfb8aa3b, v88
	v_exp_f32_e32 v83, v83
	s_nop 0
	v_add_f32_e32 v83, 1.0, v83
	v_rcp_f32_e32 v86, v83
	v_mul_f32_e32 v83, 0xbfb8aa3b, v89
	v_exp_f32_e32 v83, v83
	s_nop 0
	v_add_f32_e32 v83, 1.0, v83
	v_rcp_f32_e32 v87, v83
	s_nop 0
	v_pk_mul_f32 v[86:87], v[88:89], v[86:87]
	s_nop 0
	v_pk_mul_f32 v[84:85], v[84:85], v[86:87]
	s_nop 0
	v_cvt_pk_bf16_f32 v83, v84, v85
	flat_store_dwordx2 v[114:115], v[82:83] offset:128
	v_mul_f32_e32 v82, 0xbfb8aa3b, v78
	v_mul_f32_e32 v83, 0xbfb8aa3b, v79
	v_exp_f32_e32 v82, v82
	v_exp_f32_e32 v83, v83
	v_add_f32_e32 v82, 1.0, v82
	v_add_f32_e32 v83, 1.0, v83
	v_rcp_f32_e32 v82, v82
	v_rcp_f32_e32 v83, v83
	s_nop 0
	v_pk_mul_f32 v[78:79], v[78:79], v[82:83]
	s_nop 0
	v_pk_mul_f32 v[74:75], v[74:75], v[78:79]
	s_nop 0
	v_cvt_pk_bf16_f32 v74, v74, v75
	v_mul_f32_e32 v75, 0xbfb8aa3b, v80
	v_exp_f32_e32 v75, v75
	s_nop 0
	v_add_f32_e32 v75, 1.0, v75
	v_rcp_f32_e32 v78, v75
	v_mul_f32_e32 v75, 0xbfb8aa3b, v81
	v_exp_f32_e32 v75, v75
	s_nop 0
	v_add_f32_e32 v75, 1.0, v75
	v_rcp_f32_e32 v79, v75
	s_nop 0
	v_pk_mul_f32 v[78:79], v[80:81], v[78:79]
	s_nop 0
	v_pk_mul_f32 v[76:77], v[76:77], v[78:79]
	s_nop 0
	v_cvt_pk_bf16_f32 v75, v76, v77
	flat_store_dwordx2 v[106:107], v[74:75] offset:128
	v_mul_f32_e32 v74, 0xbfb8aa3b, v70
	v_mul_f32_e32 v75, 0xbfb8aa3b, v71
	v_exp_f32_e32 v74, v74
	v_exp_f32_e32 v75, v75
	v_add_f32_e32 v74, 1.0, v74
	v_add_f32_e32 v75, 1.0, v75
	v_rcp_f32_e32 v74, v74
	v_rcp_f32_e32 v75, v75
	s_nop 0
	v_pk_mul_f32 v[70:71], v[70:71], v[74:75]
	s_nop 0
	v_pk_mul_f32 v[66:67], v[66:67], v[70:71]
	s_nop 0
	v_cvt_pk_bf16_f32 v66, v66, v67
	v_mul_f32_e32 v67, 0xbfb8aa3b, v72
	v_exp_f32_e32 v67, v67
	s_nop 0
	v_add_f32_e32 v67, 1.0, v67
	v_rcp_f32_e32 v70, v67
	v_mul_f32_e32 v67, 0xbfb8aa3b, v73
	v_exp_f32_e32 v67, v67
	s_nop 0
	v_add_f32_e32 v67, 1.0, v67
	v_rcp_f32_e32 v71, v67
	s_nop 0
	v_pk_mul_f32 v[70:71], v[72:73], v[70:71]
	s_nop 0
	v_pk_mul_f32 v[68:69], v[68:69], v[70:71]
	s_nop 0
	v_cvt_pk_bf16_f32 v67, v68, v69
	flat_store_dwordx2 v[98:99], v[66:67] offset:128
	v_mul_f32_e32 v66, 0xbfb8aa3b, v62
	v_mul_f32_e32 v67, 0xbfb8aa3b, v63
	v_exp_f32_e32 v66, v66
	v_exp_f32_e32 v67, v67
	v_add_u32_e32 v68, 0x80, v132
	v_add_f32_e32 v66, 1.0, v66
	v_add_f32_e32 v67, 1.0, v67
	v_rcp_f32_e32 v66, v66
	v_rcp_f32_e32 v67, v67
	s_nop 0
	v_pk_mul_f32 v[62:63], v[62:63], v[66:67]
	s_nop 0
	v_pk_mul_f32 v[58:59], v[58:59], v[62:63]
	s_nop 0
	v_cvt_pk_bf16_f32 v62, v58, v59
	v_mul_f32_e32 v58, 0xbfb8aa3b, v64
	v_mul_f32_e32 v59, 0xbfb8aa3b, v65
	v_exp_f32_e32 v58, v58
	v_exp_f32_e32 v59, v59
	v_add_f32_e32 v58, 1.0, v58
	v_add_f32_e32 v59, 1.0, v59
	v_rcp_f32_e32 v58, v58
	v_rcp_f32_e32 v59, v59
	s_nop 0
	v_pk_mul_f32 v[58:59], v[64:65], v[58:59]
	s_nop 0
	v_pk_mul_f32 v[58:59], v[60:61], v[58:59]
	v_mul_f32_e32 v60, 0xbfb8aa3b, v54
	v_mul_f32_e32 v61, 0xbfb8aa3b, v55
	v_exp_f32_e32 v60, v60
	v_exp_f32_e32 v61, v61
	v_cvt_pk_bf16_f32 v63, v58, v59
	v_mad_i64_i32 v[58:59], s[8:9], v68, s10, v[130:131]
	v_add_f32_e32 v60, 1.0, v60
	v_add_f32_e32 v61, 1.0, v61
	v_rcp_f32_e32 v60, v60
	v_rcp_f32_e32 v61, v61
	flat_store_dwordx2 v[58:59], v[62:63]
	v_add_u32_e32 v62, 0x90, v132
	v_pk_mul_f32 v[54:55], v[54:55], v[60:61]
	s_nop 0
	v_pk_mul_f32 v[50:51], v[50:51], v[54:55]
	s_nop 0
	v_cvt_pk_bf16_f32 v54, v50, v51
	v_mul_f32_e32 v50, 0xbfb8aa3b, v56
	v_mul_f32_e32 v51, 0xbfb8aa3b, v57
	v_exp_f32_e32 v50, v50
	v_exp_f32_e32 v51, v51
	v_add_f32_e32 v50, 1.0, v50
	v_add_f32_e32 v51, 1.0, v51
	v_rcp_f32_e32 v50, v50
	v_rcp_f32_e32 v51, v51
	s_nop 0
	v_pk_mul_f32 v[50:51], v[56:57], v[50:51]
	s_nop 0
	v_pk_mul_f32 v[50:51], v[52:53], v[50:51]
	v_mul_f32_e32 v52, 0xbfb8aa3b, v46
	v_mul_f32_e32 v53, 0xbfb8aa3b, v47
	v_exp_f32_e32 v52, v52
	v_exp_f32_e32 v53, v53
	v_cvt_pk_bf16_f32 v55, v50, v51
	v_mad_i64_i32 v[50:51], s[8:9], v62, s10, v[130:131]
	v_add_f32_e32 v52, 1.0, v52
	v_add_f32_e32 v53, 1.0, v53
	v_rcp_f32_e32 v52, v52
	v_rcp_f32_e32 v53, v53
	flat_store_dwordx2 v[50:51], v[54:55]
	v_add_u32_e32 v54, 0xa0, v132
	v_pk_mul_f32 v[46:47], v[46:47], v[52:53]
	s_nop 0
	v_pk_mul_f32 v[42:43], v[42:43], v[46:47]
	s_nop 0
	v_cvt_pk_bf16_f32 v46, v42, v43
	v_mul_f32_e32 v42, 0xbfb8aa3b, v48
	v_mul_f32_e32 v43, 0xbfb8aa3b, v49
	v_exp_f32_e32 v42, v42
	v_exp_f32_e32 v43, v43
	v_add_f32_e32 v42, 1.0, v42
	v_add_f32_e32 v43, 1.0, v43
	v_rcp_f32_e32 v42, v42
	v_rcp_f32_e32 v43, v43
	s_nop 0
	v_pk_mul_f32 v[42:43], v[48:49], v[42:43]
	s_nop 0
	v_pk_mul_f32 v[42:43], v[44:45], v[42:43]
	v_mul_f32_e32 v44, 0xbfb8aa3b, v38
	v_mul_f32_e32 v45, 0xbfb8aa3b, v39
	v_exp_f32_e32 v44, v44
	v_exp_f32_e32 v45, v45
	v_cvt_pk_bf16_f32 v47, v42, v43
	v_mad_i64_i32 v[42:43], s[8:9], v54, s10, v[130:131]
	v_add_f32_e32 v44, 1.0, v44
	v_add_f32_e32 v45, 1.0, v45
	v_rcp_f32_e32 v44, v44
	v_rcp_f32_e32 v45, v45
	flat_store_dwordx2 v[42:43], v[46:47]
	v_add_u32_e32 v46, 0xb0, v132
	v_pk_mul_f32 v[38:39], v[38:39], v[44:45]
	s_nop 0
	v_pk_mul_f32 v[34:35], v[34:35], v[38:39]
	s_nop 0
	v_cvt_pk_bf16_f32 v38, v34, v35
	v_mul_f32_e32 v34, 0xbfb8aa3b, v40
	v_mul_f32_e32 v35, 0xbfb8aa3b, v41
	v_exp_f32_e32 v34, v34
	v_exp_f32_e32 v35, v35
	v_add_f32_e32 v34, 1.0, v34
	v_add_f32_e32 v35, 1.0, v35
	v_rcp_f32_e32 v34, v34
	v_rcp_f32_e32 v35, v35
	s_nop 0
	v_pk_mul_f32 v[34:35], v[40:41], v[34:35]
	s_nop 0
	v_pk_mul_f32 v[34:35], v[36:37], v[34:35]
	v_mul_f32_e32 v36, 0xbfb8aa3b, v30
	v_mul_f32_e32 v37, 0xbfb8aa3b, v31
	v_exp_f32_e32 v36, v36
	v_exp_f32_e32 v37, v37
	v_cvt_pk_bf16_f32 v39, v34, v35
	v_mad_i64_i32 v[34:35], s[8:9], v46, s10, v[130:131]
	v_add_f32_e32 v36, 1.0, v36
	v_add_f32_e32 v37, 1.0, v37
	v_rcp_f32_e32 v36, v36
	v_rcp_f32_e32 v37, v37
	s_mov_b64 s[10:11], 0
	flat_store_dwordx2 v[34:35], v[38:39]
	v_pk_mul_f32 v[30:31], v[30:31], v[36:37]
	s_nop 0
	v_pk_mul_f32 v[26:27], v[26:27], v[30:31]
	s_nop 0
	v_cvt_pk_bf16_f32 v26, v26, v27
	v_mul_f32_e32 v27, 0xbfb8aa3b, v32
	v_exp_f32_e32 v27, v27
	s_nop 0
	v_add_f32_e32 v27, 1.0, v27
	v_rcp_f32_e32 v30, v27
	v_mul_f32_e32 v27, 0xbfb8aa3b, v33
	v_exp_f32_e32 v27, v27
	s_nop 0
	v_add_f32_e32 v27, 1.0, v27
	v_rcp_f32_e32 v31, v27
	s_nop 0
	v_pk_mul_f32 v[30:31], v[32:33], v[30:31]
	s_nop 0
	v_pk_mul_f32 v[28:29], v[28:29], v[30:31]
	s_nop 0
	v_cvt_pk_bf16_f32 v27, v28, v29
	flat_store_dwordx2 v[58:59], v[26:27] offset:128
	v_mul_f32_e32 v26, 0xbfb8aa3b, v22
	v_mul_f32_e32 v27, 0xbfb8aa3b, v23
	v_exp_f32_e32 v26, v26
	v_exp_f32_e32 v27, v27
	v_add_f32_e32 v26, 1.0, v26
	v_add_f32_e32 v27, 1.0, v27
	v_rcp_f32_e32 v26, v26
	v_rcp_f32_e32 v27, v27
	s_nop 0
	v_pk_mul_f32 v[22:23], v[22:23], v[26:27]
	s_nop 0
	v_pk_mul_f32 v[18:19], v[18:19], v[22:23]
	s_nop 0
	v_cvt_pk_bf16_f32 v18, v18, v19
	v_mul_f32_e32 v19, 0xbfb8aa3b, v24
	v_exp_f32_e32 v19, v19
	s_nop 0
	v_add_f32_e32 v19, 1.0, v19
	v_rcp_f32_e32 v22, v19
	v_mul_f32_e32 v19, 0xbfb8aa3b, v25
	v_exp_f32_e32 v19, v19
	s_nop 0
	v_add_f32_e32 v19, 1.0, v19
	v_rcp_f32_e32 v23, v19
	s_nop 0
	v_pk_mul_f32 v[22:23], v[24:25], v[22:23]
	s_nop 0
	v_pk_mul_f32 v[20:21], v[20:21], v[22:23]
	s_nop 0
	v_cvt_pk_bf16_f32 v19, v20, v21
	flat_store_dwordx2 v[50:51], v[18:19] offset:128
	v_mul_f32_e32 v18, 0xbfb8aa3b, v14
	v_mul_f32_e32 v19, 0xbfb8aa3b, v15
	v_exp_f32_e32 v18, v18
	v_exp_f32_e32 v19, v19
	v_add_f32_e32 v18, 1.0, v18
	v_add_f32_e32 v19, 1.0, v19
	v_rcp_f32_e32 v18, v18
	v_rcp_f32_e32 v19, v19
	s_nop 0
	v_pk_mul_f32 v[14:15], v[14:15], v[18:19]
	s_nop 0
	v_pk_mul_f32 v[10:11], v[10:11], v[14:15]
	s_nop 0
	v_cvt_pk_bf16_f32 v10, v10, v11
	v_mul_f32_e32 v11, 0xbfb8aa3b, v16
	v_exp_f32_e32 v11, v11
	s_nop 0
	v_add_f32_e32 v11, 1.0, v11
	v_rcp_f32_e32 v14, v11
	v_mul_f32_e32 v11, 0xbfb8aa3b, v17
	v_exp_f32_e32 v11, v11
	s_nop 0
	v_add_f32_e32 v11, 1.0, v11
	v_rcp_f32_e32 v15, v11
	s_nop 0
	v_pk_mul_f32 v[14:15], v[16:17], v[14:15]
	s_nop 0
	v_pk_mul_f32 v[12:13], v[12:13], v[14:15]
	s_nop 0
	v_cvt_pk_bf16_f32 v11, v12, v13
	flat_store_dwordx2 v[42:43], v[10:11] offset:128
	v_mul_f32_e32 v10, 0xbfb8aa3b, v6
	v_mul_f32_e32 v11, 0xbfb8aa3b, v7
	v_exp_f32_e32 v10, v10
	v_exp_f32_e32 v11, v11
	v_add_f32_e32 v10, 1.0, v10
	v_add_f32_e32 v11, 1.0, v11
	v_rcp_f32_e32 v10, v10
	v_rcp_f32_e32 v11, v11
	s_nop 0
	v_pk_mul_f32 v[6:7], v[6:7], v[10:11]
	s_nop 0
	v_pk_mul_f32 v[2:3], v[2:3], v[6:7]
	s_nop 0
	v_cvt_pk_bf16_f32 v2, v2, v3
	v_mul_f32_e32 v3, 0xbfb8aa3b, v8
	v_exp_f32_e32 v3, v3
	s_nop 0
	v_add_f32_e32 v3, 1.0, v3
	v_rcp_f32_e32 v6, v3
	v_mul_f32_e32 v3, 0xbfb8aa3b, v9
	v_exp_f32_e32 v3, v3
	s_nop 0
	v_add_f32_e32 v3, 1.0, v3
	v_rcp_f32_e32 v7, v3
	s_nop 0
	v_pk_mul_f32 v[6:7], v[8:9], v[6:7]
	s_nop 0
	v_pk_mul_f32 v[4:5], v[4:5], v[6:7]
	s_nop 0
	v_cvt_pk_bf16_f32 v3, v4, v5
	flat_store_dwordx2 v[34:35], v[2:3] offset:128

.LBB0_765:
	s_or_b64 exec, exec, s[8:9]
	v_mov_b32_e32 v215, 0x3727c5ac
	v_readlane_b32 s2, v252, 61
	v_readlane_b32 s16, v252, 38
	s_mul_i32 s1, s2, 0x6000
	v_readlane_b32 s18, v252, 40
	v_readlane_b32 s20, v252, 42
	v_readlane_b32 s36, v251, 1
	v_readlane_b32 s3, v252, 62
	s_mul_hi_i32 s0, s2, 0x6000
	v_readlane_b32 s19, v252, 41
	v_readlane_b32 s21, v252, 43
	v_readlane_b32 s22, v252, 44
	v_readlane_b32 s23, v252, 45
	s_add_u32 s20, s18, s1
	v_readlane_b32 s50, v251, 15
	v_readlane_b32 s51, v251, 16
	v_readlane_b32 s24, v252, 46
	s_addc_u32 s21, s19, s0
	s_lshl_b64 s[22:23], s[2:3], 5
	s_lshl_b32 s0, s2, 2
	s_mov_b64 s[2:3], s[50:51]
	v_readlane_b32 s25, v252, 47
	s_barrier
	s_add_u32 s24, s2, 0xa180000
	s_addc_u32 s25, s3, 0
	v_writelane_b32 v253, s0, 60
	s_add_u32 s0, s2, 0x23d92200
	v_readlane_b32 s28, v252, 50
	s_addc_u32 s1, s3, 0
	v_readlane_b32 s29, v252, 51
	s_add_u32 s28, s2, 0x20880000
	v_writelane_b32 v253, s0, 54
	s_addc_u32 s29, s3, 0
	v_readlane_b32 s26, v252, 48
	v_writelane_b32 v253, s1, 55
	s_add_u32 s0, s2, 0x21980000
	s_addc_u32 s1, s3, 0
	v_writelane_b32 v253, s0, 56
	s_waitcnt vmcnt(0)
	v_mov_b32_e32 v4, v211
	v_readlane_b32 s27, v252, 49
	v_writelane_b32 v253, s1, 57
	v_and_b32_e32 v118, 63, v4
	v_readlane_b32 s0, v253, 26
	v_readlane_b32 s1, v253, 27
	s_add_u32 s0, s2, s0
	s_addc_u32 s1, s3, s1
	s_add_u32 s26, s0, 0x23f9a204
	s_movk_i32 s0, 0x17f
	v_cmp_lt_i32_e64 s[88:89], s0, v4
	s_movk_i32 s0, 0x1bf
	v_cmp_lt_u32_e64 s[8:9], s0, v4
	v_lshlrev_b32_e32 v18, 2, v118
	v_readlane_b32 s0, v252, 29
	s_addc_u32 s27, s1, 0
	v_mov_b32_e32 v19, v1
	v_add_u32_e32 v121, s0, v18
	v_cmp_eq_u32_e64 s[0:1], 63, v118
	v_ashrrev_i32_e32 v0, 6, v4
	v_cmp_lt_i32_e32 vcc, 2, v0
	v_writelane_b32 v253, s0, 40
	v_lshlrev_b32_e32 v124, 3, v0
	v_cmp_lt_i32_e64 s[52:53], 5, v0
	v_writelane_b32 v253, s1, 41
	s_mov_b32 s0, 0x2aaaaaab
	v_mul_hi_i32 v2, v4, s0
	v_lshrrev_b32_e32 v3, 31, v2
	v_ashrrev_i32_e32 v2, 5, v2
	v_add_u32_e32 v15, v2, v3
	s_movk_i32 s0, 0xff40
	v_mad_u64_u32 v[2:3], s[0:1], v15, s0, v[4:5]
	v_lshlrev_b32_e32 v3, 1, v2
	v_lshlrev_b32_e32 v2, 3, v2
	v_and_b32_e32 v3, 0x7e, v3
	s_movk_i32 s0, 0xfe00
	v_and_or_b32 v122, v2, s0, v3
	v_lshl_add_u64 v[2:3], s[2:3], 0, v[18:19]
	s_mov_b64 s[0:1], 0x1c600000
	v_lshl_add_u64 v[20:21], v[2:3], 0, s[0:1]
	v_add_u32_e32 v2, -3, v0
	v_cmp_ne_u32_e64 s[12:13], 6, v0
	v_cmp_gt_i32_e64 s[18:19], 3, v0
	v_cndmask_b32_e32 v0, v0, v2, vcc
	v_cmp_eq_u32_e64 s[0:1], 0, v0
	v_readlane_b32 s17, v252, 39
	v_mov_b32_e32 v7, 0x100
	v_cndmask_b32_e64 v6, 32, 0, s[0:1]
	s_movk_i32 s0, 0x100
	v_and_b32_e32 v17, 31, v4
	v_cndmask_b32_e64 v7, v7, 0, vcc
	v_cmp_eq_u32_e32 vcc, 2, v0
	v_cmp_gt_i32_e64 s[16:17], s0, v4
	s_movk_i32 s0, 0x80
	v_or_b32_e32 v3, v6, v17
	v_cndmask_b32_e64 v0, 0, 32, vcc
	v_cmp_gt_i32_e32 vcc, s0, v4
	v_cmp_eq_u32_e64 s[0:1], 0, v118
	v_mul_u32_u24_e32 v3, 0x610, v3
	v_add3_u32 v7, 0, v3, v7
	v_writelane_b32 v253, s0, 36
	v_or_b32_e32 v3, v0, v17
	v_bfe_u32 v2, v4, 5, 1
	v_writelane_b32 v253, s1, 37
	v_cmp_gt_u32_e64 s[0:1], 2, v118
	v_lshlrev_b32_e32 v0, 1, v3
	v_lshl_or_b32 v28, v2, 2, v6
	v_writelane_b32 v253, s0, 30
	v_lshl_add_u64 v[22:23], s[28:29], 0, v[0:1]
	v_add_u32_e32 v0, 0x100, v4
	v_writelane_b32 v253, s1, 31
	v_cmp_gt_u32_e64 s[0:1], 4, v118
	v_cndmask_b32_e32 v0, v4, v0, vcc
	v_or_b32_e32 v41, 10, v28
	v_writelane_b32 v253, s0, 32
	v_readlane_b32 s11, v252, 27
	v_readlane_b32 s34, v252, 28
	v_lshlrev_b32_e32 v125, 2, v0
	v_mov_b32_e32 v0, 0x1f80000
	v_bfrev_b32_e32 v8, 32
	v_writelane_b32 v253, s1, 33
	v_cmp_gt_u32_e64 s[0:1], 8, v118
	v_lshlrev_b32_e32 v30, 2, v41
	v_or_b32_e32 v43, 11, v28
	v_cndmask_b32_e32 v0, v0, v8, vcc
	v_writelane_b32 v253, s0, 34
	v_add_u32_e32 v141, s11, v30
	v_add_u32_e32 v142, s34, v30
	v_lshlrev_b32_e32 v30, 2, v43
	v_or_b32_e32 v45, 16, v28
	v_lshl_add_u64 v[24:25], s[2:3], 0, v[0:1]
	v_writelane_b32 v253, s1, 35
	v_cmp_gt_u32_e64 s[0:1], 16, v118
	v_lshlrev_b32_e32 v0, 7, v17
	v_add_u32_e32 v143, s11, v30
	v_add_u32_e32 v144, s34, v30
	v_lshlrev_b32_e32 v30, 2, v45
	v_or_b32_e32 v47, 17, v28
	v_writelane_b32 v253, s0, 38
	v_lshl_add_u64 v[26:27], s[28:29], 0, v[0:1]
	v_and_b32_e32 v0, 7, v4
	v_add_u32_e32 v145, s11, v30
	v_add_u32_e32 v148, s34, v30
	v_lshlrev_b32_e32 v30, 2, v47
	v_or_b32_e32 v49, 18, v28
	v_writelane_b32 v253, s1, 39
	v_cmp_gt_u32_e64 s[0:1], 32, v118
	v_bfe_u32 v29, v4, 3, 3
	v_lshlrev_b32_e32 v0, 4, v0
	v_add_u32_e32 v149, s11, v30
	v_add_u32_e32 v150, s34, v30
	v_lshlrev_b32_e32 v30, 2, v49
	v_or_b32_e32 v51, 19, v28
	v_readlane_b32 s30, v252, 52
	v_readlane_b32 s31, v252, 53
	v_writelane_b32 v253, s0, 42
	v_lshl_or_b32 v0, v29, 7, v0
	v_add_u32_e32 v151, s11, v30
	v_add_u32_e32 v152, s34, v30
	v_lshlrev_b32_e32 v30, 2, v51
	v_or_b32_e32 v53, 24, v28
	v_or_b32_e32 v59, 27, v28
	v_writelane_b32 v253, s1, 43
	v_cmp_le_u32_e64 s[30:31], v3, v28
	v_lshlrev_b32_e32 v8, 2, v28
	v_lshl_add_u64 v[12:13], s[2:3], 0, v[0:1]
	v_cmp_lt_u32_e64 s[0:1], v3, v28
	v_lshlrev_b32_e32 v0, 6, v28
	v_or_b32_e32 v31, 1, v28
	v_or_b32_e32 v33, 2, v28
	v_or_b32_e32 v35, 3, v28
	v_or_b32_e32 v37, 8, v28
	v_or_b32_e32 v39, 9, v28
	v_add_u32_e32 v153, s11, v30
	v_add_u32_e32 v154, s34, v30
	v_lshlrev_b32_e32 v30, 2, v53
	v_or_b32_e32 v55, 25, v28
	v_or_b32_e32 v57, 26, v28
	v_lshlrev_b32_e32 v28, 2, v59
	v_add_u32_e32 v155, s11, v30
	v_add_u32_e32 v156, s34, v30
	v_lshlrev_b32_e32 v30, 2, v55
	v_add_u32_e32 v161, s11, v28
	v_add_u32_e32 v162, s34, v28
	v_or_b32_e32 v28, 64, v118
	v_writelane_b32 v253, s0, 28
	v_add_u32_e32 v157, s11, v30
	v_add_u32_e32 v158, s34, v30
	v_lshlrev_b32_e32 v30, 2, v57
	v_lshrrev_b32_e32 v32, 5, v28
	v_writelane_b32 v253, s1, 29
	v_readlane_b32 s0, v252, 30
	v_add_u32_e32 v159, s11, v30
	v_add_u32_e32 v160, s34, v30
	v_mul_u32_u24_e32 v28, 0x110, v2
	v_mul_u32_u24_e32 v30, 0x110, v32
	v_lshlrev_b32_e32 v17, 2, v17
	v_add3_u32 v163, s0, v28, v17
	v_add3_u32 v164, s0, v30, v17
	v_or_b32_e32 v28, 0xc0, v118
	v_or_b32_e32 v30, 0x80, v118
	v_lshrrev_b32_e32 v36, 5, v28
	v_lshrrev_b32_e32 v34, 5, v30
	v_mul_u32_u24_e32 v28, 0x110, v34
	v_mul_u32_u24_e32 v30, 0x110, v36
	v_add3_u32 v165, s0, v28, v17
	v_add3_u32 v166, s0, v30, v17
	v_or_b32_e32 v28, 0x140, v118
	v_or_b32_e32 v30, 0x100, v118
	v_lshrrev_b32_e32 v40, 5, v28
	v_lshrrev_b32_e32 v38, 5, v30
	v_mul_u32_u24_e32 v28, 0x110, v38
	v_mul_u32_u24_e32 v30, 0x110, v40
	v_add3_u32 v167, s0, v28, v17
	v_add3_u32 v168, s0, v30, v17
	v_or_b32_e32 v28, 0x1c0, v118
	v_or_b32_e32 v30, 0x180, v118
	v_lshrrev_b32_e32 v44, 5, v28
	v_lshrrev_b32_e32 v42, 5, v30
	v_mul_u32_u24_e32 v28, 0x110, v42
	v_mul_u32_u24_e32 v30, 0x110, v44
	v_add3_u32 v169, s0, v28, v17
	v_add3_u32 v170, s0, v30, v17
	v_or_b32_e32 v28, 0x240, v118
	v_or_b32_e32 v30, 0x200, v118
	v_lshrrev_b32_e32 v48, 5, v28
	v_lshrrev_b32_e32 v46, 5, v30
	v_mul_u32_u24_e32 v28, 0x110, v46
	v_mul_u32_u24_e32 v30, 0x110, v48
	v_add3_u32 v171, s0, v28, v17
	v_add3_u32 v172, s0, v30, v17
	v_or_b32_e32 v28, 0x2c0, v118
	v_or_b32_e32 v30, 0x280, v118
	v_lshrrev_b32_e32 v52, 5, v28
	v_lshrrev_b32_e32 v50, 5, v30
	v_mul_u32_u24_e32 v28, 0x110, v50
	v_mul_u32_u24_e32 v30, 0x110, v52
	v_add3_u32 v173, s0, v28, v17
	v_add3_u32 v174, s0, v30, v17
	v_or_b32_e32 v28, 0x340, v118
	v_or_b32_e32 v30, 0x300, v118
	v_lshrrev_b32_e32 v56, 5, v28
	v_lshrrev_b32_e32 v54, 5, v30
	v_mul_u32_u24_e32 v28, 0x110, v54
	v_mul_u32_u24_e32 v30, 0x110, v56
	v_add3_u32 v175, s0, v28, v17
	v_add3_u32 v176, s0, v30, v17
	v_or_b32_e32 v28, 0x3c0, v118
	v_or_b32_e32 v30, 0x380, v118
	v_lshrrev_b32_e32 v60, 5, v28
	v_lshrrev_b32_e32 v58, 5, v30
	v_mul_u32_u24_e32 v6, 0x110, v3
	v_mul_u32_u24_e32 v28, 0x110, v58
	v_mul_u32_u24_e32 v30, 0x110, v60
	v_add3_u32 v130, s0, v6, v8
	v_add3_u32 v177, s0, v28, v17
	v_add3_u32 v178, s0, v30, v17
	s_mov_b32 s0, 0xbc00
	v_lshlrev_b32_e32 v123, 5, v15
	v_mul_lo_u32 v15, v15, s0
	s_add_i32 s0, 0, 0x100
	v_lshl_add_u32 v182, v29, 1, s0
	s_mov_b64 s[0:1], 0x1e680000
	v_lshl_add_u64 v[28:29], v[12:13], 0, s[0:1]
	v_cmp_lt_u32_e64 s[0:1], v3, v33
	v_cmp_lt_u32_e64 s[2:3], v3, v49
	v_add_u32_e32 v128, s11, v8
	v_writelane_b32 v253, s0, 48
	v_add_u32_e32 v129, s34, v8
	v_lshlrev_b32_e32 v6, 2, v31
	v_writelane_b32 v253, s1, 49
	v_cmp_lt_u32_e64 s[0:1], v3, v35
	v_lshlrev_b32_e32 v8, 2, v33
	v_lshlrev_b32_e32 v10, 2, v35
	v_writelane_b32 v253, s0, 50
	v_lshlrev_b32_e32 v14, 2, v37
	v_lshlrev_b32_e32 v16, 2, v39
	v_writelane_b32 v253, s1, 51
	v_cmp_lt_u32_e64 s[0:1], v3, v37
	v_readlane_b32 s37, v251, 2
	v_readlane_b32 s38, v251, 3
	v_writelane_b32 v253, s0, 44
	v_readlane_b32 s39, v251, 4
	v_readlane_b32 s42, v251, 7
	v_writelane_b32 v253, s1, 45
	v_cmp_lt_u32_e64 s[0:1], v3, v39
	v_readlane_b32 s43, v251, 8
	v_readlane_b32 s46, v251, 11
	v_writelane_b32 v253, s0, 46
	v_readlane_b32 s47, v251, 12
	v_lshlrev_b32_e32 v5, 1, v118
	v_writelane_b32 v253, s1, 47
	v_cmp_lt_u32_e64 s[0:1], v3, v41
	v_lshlrev_b32_e32 v9, 4, v2
	v_mad_u32_u24 v11, v3, s4, 0
	v_writelane_b32 v253, s0, 52
	v_and_b32_e32 v127, 0x7f, v4
	v_add_u32_e32 v131, s11, v6
	v_writelane_b32 v253, s1, 53
	v_cmp_lt_u32_e64 s[0:1], v3, v43
	v_add_u32_e32 v132, s34, v6
	v_lshlrev_b32_e32 v6, 6, v31
	v_writelane_b32 v253, s0, 12
	v_add_u32_e32 v133, s11, v8
	v_add_u32_e32 v134, s34, v8
	v_writelane_b32 v253, s1, 13
	v_cmp_lt_u32_e64 s[0:1], v3, v45
	v_lshlrev_b32_e32 v8, 6, v33
	v_add_u32_e32 v135, s11, v10
	v_writelane_b32 v253, s0, 14
	v_add_u32_e32 v136, s34, v10
	v_lshlrev_b32_e32 v10, 6, v35
	v_writelane_b32 v253, s1, 15
	v_cmp_lt_u32_e64 s[0:1], v3, v47
	v_add_u32_e32 v137, s11, v14
	v_add_u32_e32 v138, s34, v14
	v_writelane_b32 v253, s0, 16
	v_lshlrev_b32_e32 v14, 6, v37
	v_add_u32_e32 v139, s11, v16
	v_writelane_b32 v253, s1, 17
	v_writelane_b32 v253, s2, 18
	v_add_u32_e32 v140, s34, v16
	v_lshlrev_b32_e32 v16, 6, v39
	v_writelane_b32 v253, s3, 19
	v_cmp_lt_u32_e64 s[2:3], v3, v51
	v_lshlrev_b32_e32 v74, 6, v41
	v_lshlrev_b32_e32 v76, 6, v43
	v_writelane_b32 v254, s2, 2
	v_lshlrev_b32_e32 v78, 6, v45
	v_lshlrev_b32_e32 v80, 6, v47
	v_writelane_b32 v254, s3, 3
	v_cmp_lt_u32_e64 s[2:3], v3, v53
	v_lshlrev_b32_e32 v82, 6, v49
	v_lshlrev_b32_e32 v84, 6, v51
	v_writelane_b32 v253, s2, 62
	v_lshlrev_b32_e32 v86, 6, v53
	v_lshlrev_b32_e32 v88, 6, v55
	v_writelane_b32 v253, s3, 63
	v_cmp_lt_u32_e64 s[2:3], v3, v55
	v_lshlrev_b32_e32 v90, 6, v57
	v_lshlrev_b32_e32 v92, 6, v59
	v_writelane_b32 v254, s2, 0
	v_lshlrev_b32_e32 v4, 3, v4
	v_add_u32_e32 v119, s11, v18
	v_writelane_b32 v254, s3, 1
	v_cmp_lt_u32_e64 s[2:3], v3, v57
	v_add_u32_e32 v120, s34, v18
	v_lshl_add_u32 v19, v3, 2, s11
	v_writelane_b32 v253, s2, 58
	v_add_u32_e32 v126, 0, v125
	v_add3_u32 v179, v15, v4, 0
	v_or_b32_e32 v180, 0xffffffc0, v118
	v_lshlrev_b32_e32 v181, 3, v118
	v_lshlrev_b32_e32 v183, 2, v5
	v_lshlrev_b32_e32 v30, 1, v2
	v_lshlrev_b32_e32 v32, 1, v32
	v_lshlrev_b32_e32 v34, 1, v34
	v_lshlrev_b32_e32 v36, 1, v36
	v_lshlrev_b32_e32 v38, 1, v38
	v_lshlrev_b32_e32 v40, 1, v40
	v_lshlrev_b32_e32 v42, 1, v42
	v_lshlrev_b32_e32 v44, 1, v44
	v_lshlrev_b32_e32 v46, 1, v46
	v_lshlrev_b32_e32 v48, 1, v48
	v_lshlrev_b32_e32 v50, 1, v50
	v_lshlrev_b32_e32 v52, 1, v52
	v_lshlrev_b32_e32 v54, 1, v54
	v_lshlrev_b32_e32 v56, 1, v56
	v_lshlrev_b32_e32 v58, 1, v58
	v_lshlrev_b32_e32 v60, 1, v60
	v_add_u32_e32 v184, v7, v9
	v_add_u32_e32 v185, v11, v9
	v_lshlrev_b32_e32 v62, 1, v0
	v_lshlrev_b32_e32 v64, 1, v6
	v_lshlrev_b32_e32 v66, 1, v8
	v_lshlrev_b32_e32 v68, 1, v10
	v_lshlrev_b32_e32 v70, 1, v14
	v_lshlrev_b32_e32 v72, 1, v16
	v_lshlrev_b32_e32 v74, 1, v74
	v_lshlrev_b32_e32 v76, 1, v76
	v_lshlrev_b32_e32 v78, 1, v78
	v_lshlrev_b32_e32 v80, 1, v80
	v_lshlrev_b32_e32 v82, 1, v82
	v_lshlrev_b32_e32 v84, 1, v84
	v_lshlrev_b32_e32 v86, 1, v86
	v_lshlrev_b32_e32 v88, 1, v88
	v_lshlrev_b32_e32 v90, 1, v90
	v_lshlrev_b32_e32 v92, 1, v92
	v_cmp_le_u32_e64 s[36:37], v3, v31
	v_cmp_le_u32_e64 s[38:39], v3, v33
	v_cmp_le_u32_e64 s[42:43], v3, v35
	v_cmp_le_u32_e64 s[46:47], v3, v37
	v_cmp_le_u32_e64 s[50:51], v3, v39
	v_cmp_le_u32_e64 s[54:55], v3, v41
	v_cmp_le_u32_e64 s[72:73], v3, v43
	v_cmp_le_u32_e64 s[76:77], v3, v45
	v_cmp_le_u32_e64 s[80:81], v3, v47
	v_cmp_le_u32_e64 s[0:1], v3, v49
	v_cmp_le_u32_e64 s[74:75], v3, v51
	v_cmp_le_u32_e64 s[78:79], v3, v53
	v_cmp_le_u32_e64 s[82:83], v3, v55
	v_cmp_le_u32_e64 s[86:87], v3, v57
	v_writelane_b32 v253, s3, 59
	v_cmp_le_u32_e64 s[90:91], v3, v59
	v_cmp_lt_u32_e64 s[92:93], v3, v59
	s_mov_b64 s[28:29], 0
	v_readlane_b32 s40, v251, 5
	v_readlane_b32 s41, v251, 6
	v_readlane_b32 s44, v251, 9
	v_readlane_b32 s45, v251, 10
	v_readlane_b32 s48, v251, 13
	v_readlane_b32 s49, v251, 14
	s_mov_b32 s100, 0
	s_branch .LBB0_768

.LBB0_768:
	s_barrier
	s_mov_b64 s[2:3], exec
	v_readlane_b32 s34, v251, 19
	v_readlane_b32 s35, v251, 20
	s_and_b64 s[34:35], s[2:3], s[34:35]
	s_mov_b64 exec, s[34:35]
	s_cbranch_execz .LBB0_770
	s_cmp_eq_u32 s100, 0
	s_cbranch_scc1 .Ldpq_atomic
	s_waitcnt vmcnt(0)
	v_mov_b32_e32 v0, v125
	s_branch .Ldpq_have
.Ldpq_atomic:
	v_mov_b64_e32 v[2:3], s[26:27]
	flat_atomic_add v0, v[2:3], v213 sc0
.Ldpq_have:
	s_mov_b64 s[34:35], src_shared_base
	s_cmp_lg_u32 s10, -1
	s_cselect_b32 s34, s10, 0
	s_cselect_b32 s35, s35, 0
	v_mov_b32_e32 v2, s34
	v_mov_b32_e32 v3, s35
	s_waitcnt vmcnt(0) lgkmcnt(0)
	flat_store_dword v[2:3], v0 sc0 sc1
	s_waitcnt vmcnt(0)
.LBB0_770:
	s_or_b64 exec, exec, s[2:3]
	s_mov_b64 s[2:3], src_shared_base
	s_cmp_lg_u32 s10, -1
	s_cselect_b32 s2, s10, 0
	s_cselect_b32 s3, s3, 0
	v_mov_b32_e32 v2, s2
	v_mov_b32_e32 v3, s3
	s_waitcnt lgkmcnt(0)
	s_barrier
	flat_load_dword v96, v[2:3] sc0 sc1
	s_waitcnt vmcnt(0)
	s_movk_i32 s2, 0x880
	s_waitcnt lgkmcnt(0)
	v_cmp_gt_i32_e32 vcc, s2, v96
	s_mov_b64 s[2:3], -1
	s_and_saveexec_b64 s[34:35], vcc
	s_cbranch_execz .LBB0_767
	v_readlane_b32 s48, v251, 19
	v_readlane_b32 s49, v251, 20
	s_mov_b64 s[44:45], exec
	s_nop 3
	s_and_b64 exec, exec, s[48:49]
	global_atomic_add v125, v1, v213, s[26:27] sc0
	s_mov_b64 exec, s[44:45]
	s_mov_b32 s100, 1
	s_movk_i32 s2, 0x7ff
	s_movk_i32 s11, 0x800
	v_cmp_lt_i32_e64 s[2:3], s2, v96
	v_cmp_gt_i32_e32 vcc, s11, v96
	s_and_saveexec_b64 s[40:41], vcc
	s_xor_b64 s[40:41], exec, s[40:41]
	v_ashrrev_i32_e32 v2, 8, v96
	v_lshlrev_b32_e32 v4, 6, v96
	v_lshrrev_b32_e32 v3, 6, v96
	v_lshlrev_b32_e32 v0, 12, v2
	v_and_b32_e32 v9, 0xfc0, v4
	s_or_saveexec_b64 s[40:41], s[40:41]
	v_mov_b32_e32 v186, 64
	s_xor_b64 exec, exec, s[40:41]
	v_add_u32_e32 v0, 0xfffff800, v96
	v_lshrrev_b32_e32 v2, 2, v0
	v_mov_b32_e32 v0, 0x8000
	v_lshl_add_u32 v0, v2, 4, v0
	v_mov_b32_e32 v186, 16
	v_mov_b32_e32 v9, 0
	v_mov_b32_e32 v3, v96
	s_or_b64 exec, exec, s[40:41]
	v_and_b32_e32 v5, 3, v3
	v_add_u32_e32 v94, v0, v9
	s_and_saveexec_b64 s[40:41], s[88:89]
	s_xor_b64 s[40:41], exec, s[40:41]
	s_cbranch_execz .LBB0_782
	s_and_saveexec_b64 s[44:45], s[8:9]
	s_cbranch_execz .LBB0_781
	v_cmp_lt_u32_e32 vcc, v118, v186
	v_mov_b32_e32 v0, 0
	v_mov_b32_e32 v2, 0
	s_and_saveexec_b64 s[48:49], vcc
	s_cbranch_execz .LBB0_779
	v_add_u32_e32 v2, v94, v118
	v_ashrrev_i32_e32 v3, 31, v2
	v_readlane_b32 s56, v253, 54
	v_readlane_b32 s5, v253, 60
	v_lshlrev_b64 v[2:3], 5, v[2:3]
	v_readlane_b32 s57, v253, 55
	v_or_b32_e32 v6, s5, v5
	v_ashrrev_i32_e32 v7, 31, v6
	v_lshl_add_u64 v[2:3], s[56:57], 0, v[2:3]
	v_readlane_b32 s56, v252, 38
	v_lshlrev_b64 v[6:7], 2, v[6:7]
	v_readlane_b32 s62, v252, 44
	v_readlane_b32 s63, v252, 45
	v_lshlrev_b32_e32 v0, 2, v5
	v_readlane_b32 s60, v252, 42
	v_readlane_b32 s61, v252, 43
	v_lshl_add_u64 v[8:9], s[62:63], 0, v[6:7]
	v_lshl_add_u64 v[2:3], v[2:3], 0, v[0:1]
	global_load_dword v0, v[8:9], off
	v_lshl_add_u64 v[6:7], s[60:61], 0, v[6:7]
	global_load_dword v4, v[6:7], off
	s_nop 0
	flat_load_dword v6, v[2:3]
	s_nop 0
	flat_load_dword v2, v[2:3] offset:16
	s_mov_b32 s11, 0xbfb8aa3b
	v_readlane_b32 s57, v252, 39
	v_readlane_b32 s58, v252, 40
	v_readlane_b32 s59, v252, 41
	v_readlane_b32 s64, v252, 46
	v_readlane_b32 s65, v252, 47
	v_readlane_b32 s66, v252, 48
	v_readlane_b32 s67, v252, 49
	v_readlane_b32 s68, v252, 50
	v_readlane_b32 s69, v252, 51
	v_readlane_b32 s70, v252, 52
	v_readlane_b32 s71, v252, 53
	s_waitcnt vmcnt(0)
	v_mul_f32_e32 v3, 0x3fb8aa3b, v4
	s_waitcnt lgkmcnt(0)
	v_add_f32_e32 v0, v6, v0
	v_mul_f32_e64 v4, |v0|, s11
	v_exp_f32_e32 v4, v4
	v_mul_f32_e32 v2, 0xbfb8aa3b, v2
	v_exp_f32_e32 v2, v2
	s_mov_b32 s11, 0x3f317217
	v_add_f32_e32 v4, 1.0, v4
	v_cmp_gt_f32_e32 vcc, s33, v4
	v_exp_f32_e32 v3, v3
	s_nop 0
	v_cndmask_b32_e64 v6, 0, 32, vcc
	v_ldexp_f32 v4, v4, v6
	v_log_f32_e32 v4, v4
	v_max_f32_e32 v6, 0, v0
	v_add_f32_e32 v0, 1.0, v2
	v_mov_b32_e32 v2, 0x41b17218
	v_mul_f32_e32 v7, 0x3f317217, v4
	v_fma_f32 v7, v4, s11, -v7
	v_fmac_f32_e32 v7, 0x3377d1cf, v4
	s_mov_b32 s11, 0x7f800000
	v_cndmask_b32_e32 v2, 0, v2, vcc
	v_fmac_f32_e32 v7, 0x3f317217, v4
	v_cmp_lt_f32_e64 vcc, |v4|, s11
	v_rcp_f32_e32 v0, v0
	s_nop 0
	v_cndmask_b32_e32 v4, v4, v7, vcc
	v_sub_f32_e32 v2, v4, v2
	v_add_f32_e32 v2, v6, v2
	v_mul_f32_e64 v2, v2, -v3
